# v133 + nt stores also on read-once late-consumed outputs: q projection (EpiQ), HGRN state updates (UPD), q_dec
# speedup vs baseline: 1.0034x; 1.0034x over previous
.Lxb_p2a_a:
	s_lshl_b32 s66, s22, 8
	s_add_i32 s66, s66, s42
	v_or_b32_e32 v180, s66, v190
	v_ashrrev_i32_e32 v181, 31, v180
	v_lshl_add_u64 v[130:131], v[180:181], 2, s[16:17]
	global_load_dword v132, v[130:131], off
	global_load_dword v133, v[130:131], off offset:64
	global_load_dword v134, v[130:131], off offset:128
	global_load_dword v135, v[130:131], off offset:192
	global_load_dword v136, v[130:131], off offset:512
	global_load_dword v137, v[130:131], off offset:576
	global_load_dword v138, v[130:131], off offset:640
	s_nop 0
	global_load_dword v130, v[130:131], off offset:704
	v_add_u32_e32 v131, 0x80, v180
	v_and_b32_e32 v222, 0xfcf, v180
	s_mov_b64 s[22:23], -1
	s_cmp_lt_i32 s57, 2
	v_or_b32_e32 v219, 16, v222
	v_or_b32_e32 v216, 32, v222
	v_or_b32_e32 v215, 48, v222
	v_and_b32_e32 v209, 0xfcf, v131
	v_ashrrev_i32_e32 v213, 9, v131
	s_waitcnt vmcnt(0)
	v_fmamk_f32 v225, v132, 0x3aaaaaab, v206
	v_fmamk_f32 v223, v133, 0x3aaaaaab, v206
	v_fmamk_f32 v220, v134, 0x3aaaaaab, v206
	v_fmamk_f32 v217, v135, 0x3aaaaaab, v206
	v_fmamk_f32 v214, v136, 0x3aaaaaab, v206
	v_fmamk_f32 v212, v137, 0x3aaaaaab, v206
	v_fmamk_f32 v211, v138, 0x3aaaaaab, v206
	v_cmp_gt_f32_e64 s[8:9], s53, v225
	v_mul_f32_e32 v226, 0x4b800000, v225
	v_cmp_gt_f32_e64 s[6:7], s53, v223
	v_mul_f32_e32 v224, 0x4b800000, v223
	v_cmp_gt_f32_e64 s[4:5], s53, v220
	v_mul_f32_e32 v221, 0x4b800000, v220
	v_cmp_gt_f32_e32 vcc, s53, v217
	v_mul_f32_e32 v218, 0x4b800000, v217
	v_fmamk_f32 v210, v130, 0x3aaaaaab, v206
	s_cbranch_scc1 .LBB0_446
	v_lshlrev_b32_e32 v130, 6, v180
	v_and_b32_e32 v164, 0x3f3c0, v130
	v_lshl_add_u64 v[130:131], v[166:167], 0, v[164:165]
	global_load_dwordx4 v[228:231], v[130:131], off
	v_lshl_add_u64 v[134:135], v[168:169], 0, v[164:165]
	global_load_dwordx4 v[232:235], v[134:135], off
	global_load_dwordx4 v[146:149], v[130:131], off offset:1024
	global_load_dwordx4 v[150:153], v[134:135], off offset:1024
	global_load_dwordx4 v[138:141], v[130:131], off offset:2048
	global_load_dwordx4 v[142:145], v[134:135], off offset:2048
	s_nop 0
	global_load_dwordx4 v[130:133], v[130:131], off offset:3072
	s_nop 0
	global_load_dwordx4 v[134:137], v[134:135], off offset:3072
	v_cndmask_b32_e64 v164, v225, v226, s[8:9]
	v_rsq_f32_e32 v164, v164
	s_ashr_i32 s22, s66, 9
	s_and_b32 s22, s22, -8
	s_or_b32 s68, s22, s41
	v_mul_f32_e32 v181, 0x45800000, v164
	v_cndmask_b32_e64 v164, v164, v181, s[8:9]
	v_mul_f32_e32 v164, 0x3e16c740, v164
	s_ashr_i32 s69, s68, 31
	s_lshl_b64 s[22:23], s[68:69], 12
	v_or_b32_e32 v181, s22, v222
	s_waitcnt vmcnt(0)
	v_pk_mul_f32 v[182:183], v[122:123], v[232:233]
	v_pk_mul_f32 v[236:237], v[124:125], v[234:235]
	v_pk_mul_f32 v[238:239], v[128:129], v[234:235]
	v_pk_fma_f32 v[182:183], v[126:127], v[228:229], v[182:183] neg_lo:[0,0,1] neg_hi:[0,0,1]
	v_pk_fma_f32 v[236:237], v[128:129], v[230:231], v[236:237] neg_lo:[0,0,1] neg_hi:[0,0,1]
	v_pk_mul_f32 v[182:183], v[164:165], v[182:183] op_sel_hi:[0,1]
	v_pk_mul_f32 v[236:237], v[164:165], v[236:237] op_sel_hi:[0,1]
	v_cvt_pk_bf16_f32 v182, v182, v183
	v_cvt_pk_bf16_f32 v183, v236, v237
	v_pk_mul_f32 v[236:237], v[126:127], v[232:233]
	v_pk_fma_f32 v[238:239], v[124:125], v[230:231], v[238:239]
	v_pk_fma_f32 v[236:237], v[122:123], v[228:229], v[236:237]
	v_pk_mul_f32 v[238:239], v[164:165], v[238:239] op_sel_hi:[0,1]
	v_pk_mul_f32 v[236:237], v[164:165], v[236:237] op_sel_hi:[0,1]
	v_cvt_pk_bf16_f32 v236, v236, v237
	v_cvt_pk_bf16_f32 v237, v238, v239
	v_mad_u64_u32 v[238:239], s[8:9], v181, s54, v[172:173]
	v_mad_i32_i24 v239, s23, v207, v239
	global_store_dwordx2 v[238:239], v[182:183], off offset:128 nt
	global_store_dwordx2 v[238:239], v[236:237], off offset:160 nt
	v_pk_mul_f32 v[182:183], v[114:115], v[232:233]
	v_pk_mul_f32 v[232:233], v[118:119], v[232:233]
	s_or_b32 s8, s68, 4
	v_pk_fma_f32 v[182:183], v[118:119], v[228:229], v[182:183] neg_lo:[0,0,1] neg_hi:[0,0,1]
	v_pk_mul_f32 v[236:237], v[116:117], v[234:235]
	v_pk_fma_f32 v[228:229], v[114:115], v[228:229], v[232:233]
	v_pk_mul_f32 v[232:233], v[120:121], v[234:235]
	s_ashr_i32 s9, s8, 31
	v_pk_fma_f32 v[236:237], v[120:121], v[230:231], v[236:237] neg_lo:[0,0,1] neg_hi:[0,0,1]
	v_pk_fma_f32 v[230:231], v[116:117], v[230:231], v[232:233]
	s_lshl_b64 s[8:9], s[8:9], 12
	v_pk_mul_f32 v[182:183], v[164:165], v[182:183] op_sel_hi:[0,1]
	v_pk_mul_f32 v[236:237], v[164:165], v[236:237] op_sel_hi:[0,1]
	v_pk_mul_f32 v[228:229], v[164:165], v[228:229] op_sel_hi:[0,1]
	v_pk_mul_f32 v[230:231], v[164:165], v[230:231] op_sel_hi:[0,1]
	v_or_b32_e32 v164, s8, v222
	v_cvt_pk_bf16_f32 v228, v228, v229
	v_cvt_pk_bf16_f32 v229, v230, v231
	v_mad_u64_u32 v[230:231], s[68:69], v164, s54, v[172:173]
	v_cndmask_b32_e64 v164, v223, v224, s[6:7]
	v_rsq_f32_e32 v164, v164
	v_cvt_pk_bf16_f32 v182, v182, v183
	v_cvt_pk_bf16_f32 v183, v236, v237
	v_mad_i32_i24 v231, s9, v207, v231
	v_mul_f32_e32 v181, 0x45800000, v164
	global_store_dwordx2 v[230:231], v[182:183], off offset:128 nt
	global_store_dwordx2 v[230:231], v[228:229], off offset:160 nt
	v_cndmask_b32_e64 v164, v164, v181, s[6:7]
	v_pk_mul_f32 v[182:183], v[106:107], v[150:151]
	v_pk_mul_f32 v[228:229], v[108:109], v[152:153]
	v_mul_f32_e32 v164, 0x3e16c740, v164
	v_pk_fma_f32 v[182:183], v[110:111], v[146:147], v[182:183] neg_lo:[0,0,1] neg_hi:[0,0,1]
	v_pk_fma_f32 v[228:229], v[112:113], v[148:149], v[228:229] neg_lo:[0,0,1] neg_hi:[0,0,1]
	v_pk_mul_f32 v[182:183], v[164:165], v[182:183] op_sel_hi:[0,1]
	v_pk_mul_f32 v[228:229], v[164:165], v[228:229] op_sel_hi:[0,1]
	v_cvt_pk_bf16_f32 v182, v182, v183
	v_cvt_pk_bf16_f32 v183, v228, v229
	v_pk_mul_f32 v[228:229], v[110:111], v[150:151]
	v_pk_mul_f32 v[230:231], v[112:113], v[152:153]
	v_pk_fma_f32 v[228:229], v[106:107], v[146:147], v[228:229]
	v_pk_fma_f32 v[230:231], v[108:109], v[148:149], v[230:231]
	v_pk_mul_f32 v[228:229], v[164:165], v[228:229] op_sel_hi:[0,1]
	v_pk_mul_f32 v[230:231], v[164:165], v[230:231] op_sel_hi:[0,1]
	v_or_b32_e32 v181, s22, v219
	v_cvt_pk_bf16_f32 v228, v228, v229
	v_cvt_pk_bf16_f32 v229, v230, v231
	v_mad_u64_u32 v[230:231], s[6:7], v181, s54, v[172:173]
	v_mad_i32_i24 v231, s23, v207, v231
	global_store_dwordx2 v[230:231], v[182:183], off offset:128 nt
	global_store_dwordx2 v[230:231], v[228:229], off offset:160 nt
	v_pk_mul_f32 v[182:183], v[94:95], v[150:151]
	v_pk_mul_f32 v[150:151], v[102:103], v[150:151]
	v_pk_fma_f32 v[182:183], v[102:103], v[146:147], v[182:183] neg_lo:[0,0,1] neg_hi:[0,0,1]
	v_pk_mul_f32 v[228:229], v[96:97], v[152:153]
	v_pk_fma_f32 v[146:147], v[94:95], v[146:147], v[150:151]
	v_pk_mul_f32 v[150:151], v[104:105], v[152:153]
	v_pk_fma_f32 v[228:229], v[104:105], v[148:149], v[228:229] neg_lo:[0,0,1] neg_hi:[0,0,1]
	v_pk_fma_f32 v[148:149], v[96:97], v[148:149], v[150:151]
	v_pk_mul_f32 v[146:147], v[164:165], v[146:147] op_sel_hi:[0,1]
	v_pk_mul_f32 v[148:149], v[164:165], v[148:149] op_sel_hi:[0,1]
	v_cvt_pk_bf16_f32 v146, v146, v147
	v_cvt_pk_bf16_f32 v147, v148, v149
	v_or_b32_e32 v148, s8, v219
	v_pk_mul_f32 v[182:183], v[164:165], v[182:183] op_sel_hi:[0,1]
	v_pk_mul_f32 v[228:229], v[164:165], v[228:229] op_sel_hi:[0,1]
	v_mad_u64_u32 v[148:149], s[6:7], v148, s54, v[172:173]
	v_cvt_pk_bf16_f32 v182, v182, v183
	v_cvt_pk_bf16_f32 v183, v228, v229
	v_mad_i32_i24 v149, s9, v207, v149
	global_store_dwordx2 v[148:149], v[182:183], off offset:128 nt
	global_store_dwordx2 v[148:149], v[146:147], off offset:160 nt
	v_cndmask_b32_e64 v146, v220, v221, s[4:5]
	v_rsq_f32_e32 v146, v146
	v_pk_mul_f32 v[148:149], v[90:91], v[142:143]
	v_pk_mul_f32 v[150:151], v[92:93], v[144:145]
	v_pk_fma_f32 v[148:149], v[98:99], v[138:139], v[148:149] neg_lo:[0,0,1] neg_hi:[0,0,1]
	v_mul_f32_e32 v147, 0x45800000, v146
	v_cndmask_b32_e64 v146, v146, v147, s[4:5]
	v_mul_f32_e32 v146, 0x3e16c740, v146
	v_pk_fma_f32 v[150:151], v[100:101], v[140:141], v[150:151] neg_lo:[0,0,1] neg_hi:[0,0,1]
	v_pk_mul_f32 v[148:149], v[146:147], v[148:149] op_sel_hi:[0,1]
	v_pk_mul_f32 v[150:151], v[146:147], v[150:151] op_sel_hi:[0,1]
	v_cvt_pk_bf16_f32 v148, v148, v149
	v_cvt_pk_bf16_f32 v149, v150, v151
	v_pk_mul_f32 v[150:151], v[98:99], v[142:143]
	v_pk_mul_f32 v[152:153], v[100:101], v[144:145]
	v_pk_fma_f32 v[150:151], v[90:91], v[138:139], v[150:151]
	v_pk_fma_f32 v[152:153], v[92:93], v[140:141], v[152:153]
	v_pk_mul_f32 v[150:151], v[146:147], v[150:151] op_sel_hi:[0,1]
	v_pk_mul_f32 v[152:153], v[146:147], v[152:153] op_sel_hi:[0,1]
	v_or_b32_e32 v147, s22, v216
	v_cvt_pk_bf16_f32 v150, v150, v151
	v_cvt_pk_bf16_f32 v151, v152, v153
	v_mad_u64_u32 v[152:153], s[4:5], v147, s54, v[172:173]
	v_mad_i32_i24 v153, s23, v207, v153
	global_store_dwordx2 v[152:153], v[148:149], off offset:128 nt
	global_store_dwordx2 v[152:153], v[150:151], off offset:160 nt
	v_pk_mul_f32 v[148:149], v[78:79], v[142:143]
	v_pk_mul_f32 v[142:143], v[86:87], v[142:143]
	v_pk_fma_f32 v[148:149], v[86:87], v[138:139], v[148:149] neg_lo:[0,0,1] neg_hi:[0,0,1]
	v_pk_mul_f32 v[150:151], v[80:81], v[144:145]
	v_pk_fma_f32 v[138:139], v[78:79], v[138:139], v[142:143]
	v_pk_mul_f32 v[142:143], v[88:89], v[144:145]
	v_pk_fma_f32 v[150:151], v[88:89], v[140:141], v[150:151] neg_lo:[0,0,1] neg_hi:[0,0,1]
	v_pk_fma_f32 v[140:141], v[80:81], v[140:141], v[142:143]
	v_pk_mul_f32 v[138:139], v[146:147], v[138:139] op_sel_hi:[0,1]
	v_pk_mul_f32 v[140:141], v[146:147], v[140:141] op_sel_hi:[0,1]
	v_cvt_pk_bf16_f32 v138, v138, v139
	v_cvt_pk_bf16_f32 v139, v140, v141
	v_or_b32_e32 v140, s8, v216
	v_pk_mul_f32 v[148:149], v[146:147], v[148:149] op_sel_hi:[0,1]
	v_pk_mul_f32 v[150:151], v[146:147], v[150:151] op_sel_hi:[0,1]
	v_mad_u64_u32 v[140:141], s[4:5], v140, s54, v[172:173]
	v_cvt_pk_bf16_f32 v148, v148, v149
	v_cvt_pk_bf16_f32 v149, v150, v151
	v_mad_i32_i24 v141, s9, v207, v141
	global_store_dwordx2 v[140:141], v[148:149], off offset:128 nt
	global_store_dwordx2 v[140:141], v[138:139], off offset:160 nt
	v_cndmask_b32_e32 v138, v217, v218, vcc
	v_rsq_f32_e32 v138, v138
	v_pk_mul_f32 v[140:141], v[74:75], v[134:135]
	v_pk_mul_f32 v[142:143], v[76:77], v[136:137]
	v_pk_fma_f32 v[140:141], v[82:83], v[130:131], v[140:141] neg_lo:[0,0,1] neg_hi:[0,0,1]
	v_mul_f32_e32 v139, 0x45800000, v138
	v_cndmask_b32_e32 v138, v138, v139, vcc
	v_mul_f32_e32 v138, 0x3e16c740, v138
	v_pk_fma_f32 v[142:143], v[84:85], v[132:133], v[142:143] neg_lo:[0,0,1] neg_hi:[0,0,1]
	v_pk_mul_f32 v[140:141], v[138:139], v[140:141] op_sel_hi:[0,1]
	v_pk_mul_f32 v[142:143], v[138:139], v[142:143] op_sel_hi:[0,1]
	v_cvt_pk_bf16_f32 v140, v140, v141
	v_cvt_pk_bf16_f32 v141, v142, v143
	v_pk_mul_f32 v[142:143], v[82:83], v[134:135]
	v_pk_mul_f32 v[144:145], v[84:85], v[136:137]
	v_pk_fma_f32 v[142:143], v[74:75], v[130:131], v[142:143]
	v_pk_fma_f32 v[144:145], v[76:77], v[132:133], v[144:145]
	v_pk_mul_f32 v[142:143], v[138:139], v[142:143] op_sel_hi:[0,1]
	v_pk_mul_f32 v[144:145], v[138:139], v[144:145] op_sel_hi:[0,1]
	v_or_b32_e32 v139, s22, v215
	v_cvt_pk_bf16_f32 v142, v142, v143
	v_cvt_pk_bf16_f32 v143, v144, v145
	v_mad_u64_u32 v[144:145], s[4:5], v139, s54, v[172:173]
	v_mad_i32_i24 v145, s23, v207, v145
	global_store_dwordx2 v[144:145], v[140:141], off offset:128 nt
	global_store_dwordx2 v[144:145], v[142:143], off offset:160 nt
	v_pk_mul_f32 v[140:141], v[66:67], v[134:135]
	v_pk_mul_f32 v[134:135], v[70:71], v[134:135]
	v_pk_fma_f32 v[140:141], v[70:71], v[130:131], v[140:141] neg_lo:[0,0,1] neg_hi:[0,0,1]
	v_pk_mul_f32 v[142:143], v[68:69], v[136:137]
	v_pk_fma_f32 v[130:131], v[66:67], v[130:131], v[134:135]
	v_pk_mul_f32 v[134:135], v[72:73], v[136:137]
	v_pk_fma_f32 v[142:143], v[72:73], v[132:133], v[142:143] neg_lo:[0,0,1] neg_hi:[0,0,1]
	v_pk_fma_f32 v[132:133], v[68:69], v[132:133], v[134:135]
	v_pk_mul_f32 v[130:131], v[138:139], v[130:131] op_sel_hi:[0,1]
	v_pk_mul_f32 v[132:133], v[138:139], v[132:133] op_sel_hi:[0,1]
	v_cvt_pk_bf16_f32 v130, v130, v131
	v_cvt_pk_bf16_f32 v131, v132, v133
	v_or_b32_e32 v132, s8, v215
	v_pk_mul_f32 v[140:141], v[138:139], v[140:141] op_sel_hi:[0,1]
	v_pk_mul_f32 v[142:143], v[138:139], v[142:143] op_sel_hi:[0,1]
	v_mad_u64_u32 v[132:133], s[4:5], v132, s54, v[172:173]
	v_cvt_pk_bf16_f32 v140, v140, v141
	v_cvt_pk_bf16_f32 v141, v142, v143
	v_mad_i32_i24 v133, s9, v207, v133
	global_store_dwordx2 v[132:133], v[140:141], off offset:128 nt
	global_store_dwordx2 v[132:133], v[130:131], off offset:160 nt
	v_lshl_add_u32 v130, v180, 4, v208
	v_and_b32_e32 v130, 0xfcf0, v130
	v_lshlrev_b32_e32 v164, 2, v130
	v_lshl_add_u64 v[130:131], v[166:167], 0, v[164:165]
	global_load_dwordx4 v[228:231], v[130:131], off
	v_lshl_add_u64 v[134:135], v[168:169], 0, v[164:165]
	global_load_dwordx4 v[232:235], v[134:135], off
	global_load_dwordx4 v[146:149], v[130:131], off offset:1024
	global_load_dwordx4 v[150:153], v[134:135], off offset:1024
	global_load_dwordx4 v[138:141], v[130:131], off offset:2048
	global_load_dwordx4 v[142:145], v[134:135], off offset:2048
	s_nop 0
	global_load_dwordx4 v[130:133], v[130:131], off offset:3072
	s_nop 0
	global_load_dwordx4 v[134:137], v[134:135], off offset:3072
	v_cmp_gt_f32_e32 vcc, s53, v214
	v_mul_f32_e32 v164, 0x4b800000, v214
	v_and_or_b32 v180, v213, -8, s41
	v_cndmask_b32_e32 v164, v214, v164, vcc
	v_rsq_f32_e32 v164, v164
	v_or_b32_e32 v227, 16, v209
	v_mul_f32_e32 v181, 0x45800000, v164
	v_cndmask_b32_e32 v164, v164, v181, vcc
	v_mul_f32_e32 v164, 0x3e16c740, v164
	v_ashrrev_i32_e32 v181, 31, v180
	v_cmp_gt_f32_e32 vcc, s53, v212
	s_waitcnt vmcnt(0)
	v_pk_mul_f32 v[182:183], v[58:59], v[232:233]
	s_nop 0
	v_pk_fma_f32 v[182:183], v[62:63], v[228:229], v[182:183] neg_lo:[0,0,1] neg_hi:[0,0,1]
	s_nop 0
	v_pk_mul_f32 v[182:183], v[164:165], v[182:183] op_sel_hi:[0,1]
	v_cvt_pk_bf16_f32 v236, v182, v183
	v_pk_mul_f32 v[182:183], v[60:61], v[234:235]
	s_nop 0
	v_pk_fma_f32 v[182:183], v[64:65], v[230:231], v[182:183] neg_lo:[0,0,1] neg_hi:[0,0,1]
	s_nop 0
	v_pk_mul_f32 v[182:183], v[164:165], v[182:183] op_sel_hi:[0,1]
	v_cvt_pk_bf16_f32 v237, v182, v183
	v_pk_mul_f32 v[182:183], v[62:63], v[232:233]
	s_nop 0
	v_pk_fma_f32 v[182:183], v[58:59], v[228:229], v[182:183]
	s_nop 0
	v_pk_mul_f32 v[182:183], v[164:165], v[182:183] op_sel_hi:[0,1]
	v_cvt_pk_bf16_f32 v238, v182, v183
	v_pk_mul_f32 v[182:183], v[64:65], v[234:235]
	s_nop 0
	v_pk_fma_f32 v[182:183], v[60:61], v[230:231], v[182:183]
	s_nop 0
	v_pk_mul_f32 v[182:183], v[164:165], v[182:183] op_sel_hi:[0,1]
	v_cvt_pk_bf16_f32 v239, v182, v183
	v_lshlrev_b64 v[182:183], 12, v[180:181]
	v_or_b32_e32 v181, v182, v209
	v_mad_u64_u32 v[240:241], s[4:5], v181, s54, v[172:173]
	v_mad_i32_i24 v241, v183, s54, v241
	global_store_dwordx2 v[240:241], v[236:237], off offset:128 nt
	global_store_dwordx2 v[240:241], v[238:239], off offset:160 nt
	v_pk_mul_f32 v[236:237], v[50:51], v[232:233]
	v_pk_mul_f32 v[232:233], v[54:55], v[232:233]
	v_or_b32_e32 v180, 4, v180
	v_pk_fma_f32 v[236:237], v[54:55], v[228:229], v[236:237] neg_lo:[0,0,1] neg_hi:[0,0,1]
	v_pk_mul_f32 v[238:239], v[52:53], v[234:235]
	v_pk_fma_f32 v[228:229], v[50:51], v[228:229], v[232:233]
	v_pk_mul_f32 v[232:233], v[56:57], v[234:235]
	v_ashrrev_i32_e32 v181, 31, v180
	v_pk_fma_f32 v[238:239], v[56:57], v[230:231], v[238:239] neg_lo:[0,0,1] neg_hi:[0,0,1]
	v_pk_fma_f32 v[230:231], v[52:53], v[230:231], v[232:233]
	v_lshlrev_b64 v[180:181], 12, v[180:181]
	v_pk_mul_f32 v[236:237], v[164:165], v[236:237] op_sel_hi:[0,1]
	v_pk_mul_f32 v[238:239], v[164:165], v[238:239] op_sel_hi:[0,1]
	v_pk_mul_f32 v[228:229], v[164:165], v[228:229] op_sel_hi:[0,1]
	v_pk_mul_f32 v[230:231], v[164:165], v[230:231] op_sel_hi:[0,1]
	v_or_b32_e32 v164, v180, v209
	v_cvt_pk_bf16_f32 v228, v228, v229
	v_cvt_pk_bf16_f32 v229, v230, v231
	v_mad_u64_u32 v[230:231], s[4:5], v164, s54, v[172:173]
	v_mul_f32_e32 v164, 0x4b800000, v212
	v_cndmask_b32_e32 v164, v212, v164, vcc
	v_rsq_f32_e32 v164, v164
	v_cvt_pk_bf16_f32 v236, v236, v237
	v_cvt_pk_bf16_f32 v237, v238, v239
	v_mad_i32_i24 v231, v181, s54, v231
	global_store_dwordx2 v[230:231], v[236:237], off offset:128 nt
	global_store_dwordx2 v[230:231], v[228:229], off offset:160 nt
	v_mul_f32_e32 v228, 0x45800000, v164
	v_cndmask_b32_e32 v164, v164, v228, vcc
	v_pk_mul_f32 v[228:229], v[42:43], v[150:151]
	v_pk_mul_f32 v[230:231], v[44:45], v[152:153]
	v_mul_f32_e32 v164, 0x3e16c740, v164
	v_pk_fma_f32 v[228:229], v[46:47], v[146:147], v[228:229] neg_lo:[0,0,1] neg_hi:[0,0,1]
	v_pk_fma_f32 v[230:231], v[48:49], v[148:149], v[230:231] neg_lo:[0,0,1] neg_hi:[0,0,1]
	v_pk_mul_f32 v[228:229], v[164:165], v[228:229] op_sel_hi:[0,1]
	v_pk_mul_f32 v[230:231], v[164:165], v[230:231] op_sel_hi:[0,1]
	v_cvt_pk_bf16_f32 v228, v228, v229
	v_cvt_pk_bf16_f32 v229, v230, v231
	v_pk_mul_f32 v[230:231], v[46:47], v[150:151]
	v_pk_mul_f32 v[232:233], v[48:49], v[152:153]
	v_pk_fma_f32 v[230:231], v[42:43], v[146:147], v[230:231]
	v_pk_fma_f32 v[232:233], v[44:45], v[148:149], v[232:233]
	v_pk_mul_f32 v[230:231], v[164:165], v[230:231] op_sel_hi:[0,1]
	v_pk_mul_f32 v[232:233], v[164:165], v[232:233] op_sel_hi:[0,1]
	v_cvt_pk_bf16_f32 v230, v230, v231
	v_cvt_pk_bf16_f32 v231, v232, v233
	v_or_b32_e32 v232, v182, v227
	v_mad_u64_u32 v[232:233], s[4:5], v232, s54, v[172:173]
	v_mad_i32_i24 v233, v183, s54, v233
	global_store_dwordx2 v[232:233], v[228:229], off offset:128 nt
	global_store_dwordx2 v[232:233], v[230:231], off offset:160 nt
	v_pk_mul_f32 v[228:229], v[34:35], v[150:151]
	v_pk_mul_f32 v[150:151], v[38:39], v[150:151]
	v_pk_fma_f32 v[228:229], v[38:39], v[146:147], v[228:229] neg_lo:[0,0,1] neg_hi:[0,0,1]
	v_pk_mul_f32 v[230:231], v[36:37], v[152:153]
	v_pk_fma_f32 v[146:147], v[34:35], v[146:147], v[150:151]
	v_pk_mul_f32 v[150:151], v[40:41], v[152:153]
	v_pk_fma_f32 v[230:231], v[40:41], v[148:149], v[230:231] neg_lo:[0,0,1] neg_hi:[0,0,1]
	v_pk_fma_f32 v[148:149], v[36:37], v[148:149], v[150:151]
	v_pk_mul_f32 v[146:147], v[164:165], v[146:147] op_sel_hi:[0,1]
	v_pk_mul_f32 v[148:149], v[164:165], v[148:149] op_sel_hi:[0,1]
	v_cvt_pk_bf16_f32 v146, v146, v147
	v_cvt_pk_bf16_f32 v147, v148, v149
	v_or_b32_e32 v148, v180, v227
	v_pk_mul_f32 v[228:229], v[164:165], v[228:229] op_sel_hi:[0,1]
	v_pk_mul_f32 v[230:231], v[164:165], v[230:231] op_sel_hi:[0,1]
	v_mad_u64_u32 v[148:149], s[4:5], v148, s54, v[172:173]
	v_cvt_pk_bf16_f32 v228, v228, v229
	v_cvt_pk_bf16_f32 v229, v230, v231
	v_mad_i32_i24 v149, v181, s54, v149
	global_store_dwordx2 v[148:149], v[228:229], off offset:128 nt
	global_store_dwordx2 v[148:149], v[146:147], off offset:160 nt
	v_cmp_gt_f32_e32 vcc, s53, v211
	v_mul_f32_e32 v146, 0x4b800000, v211
	v_pk_mul_f32 v[150:151], v[28:29], v[144:145]
	v_cndmask_b32_e32 v146, v211, v146, vcc
	v_rsq_f32_e32 v146, v146
	v_or_b32_e32 v147, 32, v209
	v_pk_fma_f32 v[150:151], v[32:33], v[140:141], v[150:151] neg_lo:[0,0,1] neg_hi:[0,0,1]
	v_pk_mul_f32 v[152:153], v[32:33], v[144:145]
	v_mul_f32_e32 v148, 0x45800000, v146
	v_cndmask_b32_e32 v146, v146, v148, vcc
	v_pk_mul_f32 v[148:149], v[26:27], v[142:143]
	v_mul_f32_e32 v146, 0x3e16c740, v146
	v_pk_fma_f32 v[148:149], v[30:31], v[138:139], v[148:149] neg_lo:[0,0,1] neg_hi:[0,0,1]
	v_pk_mul_f32 v[150:151], v[146:147], v[150:151] op_sel_hi:[0,1]
	v_pk_mul_f32 v[148:149], v[146:147], v[148:149] op_sel_hi:[0,1]
	v_cvt_pk_bf16_f32 v148, v148, v149
	v_cvt_pk_bf16_f32 v149, v150, v151
	v_pk_mul_f32 v[150:151], v[30:31], v[142:143]
	v_pk_fma_f32 v[152:153], v[28:29], v[140:141], v[152:153]
	v_pk_fma_f32 v[150:151], v[26:27], v[138:139], v[150:151]
	v_pk_mul_f32 v[152:153], v[146:147], v[152:153] op_sel_hi:[0,1]
	v_pk_mul_f32 v[150:151], v[146:147], v[150:151] op_sel_hi:[0,1]
	v_cvt_pk_bf16_f32 v150, v150, v151
	v_cvt_pk_bf16_f32 v151, v152, v153
	v_or_b32_e32 v152, v182, v147
	v_mad_u64_u32 v[152:153], s[4:5], v152, s54, v[172:173]
	v_mad_i32_i24 v153, v183, s54, v153
	global_store_dwordx2 v[152:153], v[148:149], off offset:128 nt
	global_store_dwordx2 v[152:153], v[150:151], off offset:160 nt
	v_pk_mul_f32 v[148:149], v[18:19], v[142:143]
	v_pk_mul_f32 v[142:143], v[22:23], v[142:143]
	v_pk_fma_f32 v[148:149], v[22:23], v[138:139], v[148:149] neg_lo:[0,0,1] neg_hi:[0,0,1]
	v_pk_mul_f32 v[150:151], v[20:21], v[144:145]
	v_pk_fma_f32 v[138:139], v[18:19], v[138:139], v[142:143]
	v_pk_mul_f32 v[142:143], v[24:25], v[144:145]
	v_pk_fma_f32 v[150:151], v[24:25], v[140:141], v[150:151] neg_lo:[0,0,1] neg_hi:[0,0,1]
	v_pk_fma_f32 v[140:141], v[20:21], v[140:141], v[142:143]
	v_pk_mul_f32 v[138:139], v[146:147], v[138:139] op_sel_hi:[0,1]
	v_pk_mul_f32 v[140:141], v[146:147], v[140:141] op_sel_hi:[0,1]
	v_cvt_pk_bf16_f32 v138, v138, v139
	v_cvt_pk_bf16_f32 v139, v140, v141
	v_or_b32_e32 v140, v180, v147
	v_pk_mul_f32 v[148:149], v[146:147], v[148:149] op_sel_hi:[0,1]
	v_pk_mul_f32 v[150:151], v[146:147], v[150:151] op_sel_hi:[0,1]
	v_mad_u64_u32 v[140:141], s[4:5], v140, s54, v[172:173]
	v_cvt_pk_bf16_f32 v148, v148, v149
	v_cvt_pk_bf16_f32 v149, v150, v151
	v_mad_i32_i24 v141, v181, s54, v141
	global_store_dwordx2 v[140:141], v[148:149], off offset:128 nt
	global_store_dwordx2 v[140:141], v[138:139], off offset:160 nt
	v_cmp_gt_f32_e32 vcc, s53, v210
	v_mul_f32_e32 v138, 0x4b800000, v210
	v_pk_mul_f32 v[142:143], v[12:13], v[136:137]
	v_cndmask_b32_e32 v138, v210, v138, vcc
	v_rsq_f32_e32 v138, v138
	v_or_b32_e32 v139, 48, v209
	v_pk_fma_f32 v[142:143], v[16:17], v[132:133], v[142:143] neg_lo:[0,0,1] neg_hi:[0,0,1]
	v_pk_mul_f32 v[144:145], v[16:17], v[136:137]
	v_mul_f32_e32 v140, 0x45800000, v138
	v_cndmask_b32_e32 v138, v138, v140, vcc
	v_pk_mul_f32 v[140:141], v[10:11], v[134:135]
	v_mul_f32_e32 v138, 0x3e16c740, v138
	v_pk_fma_f32 v[140:141], v[14:15], v[130:131], v[140:141] neg_lo:[0,0,1] neg_hi:[0,0,1]
	v_pk_mul_f32 v[142:143], v[138:139], v[142:143] op_sel_hi:[0,1]
	v_pk_mul_f32 v[140:141], v[138:139], v[140:141] op_sel_hi:[0,1]
	v_cvt_pk_bf16_f32 v140, v140, v141
	v_cvt_pk_bf16_f32 v141, v142, v143
	v_pk_mul_f32 v[142:143], v[14:15], v[134:135]
	v_pk_fma_f32 v[144:145], v[12:13], v[132:133], v[144:145]
	v_pk_fma_f32 v[142:143], v[10:11], v[130:131], v[142:143]
	v_pk_mul_f32 v[144:145], v[138:139], v[144:145] op_sel_hi:[0,1]
	v_pk_mul_f32 v[142:143], v[138:139], v[142:143] op_sel_hi:[0,1]
	v_cvt_pk_bf16_f32 v142, v142, v143
	v_cvt_pk_bf16_f32 v143, v144, v145
	v_or_b32_e32 v144, v182, v139
	v_mad_u64_u32 v[144:145], s[4:5], v144, s54, v[172:173]
	v_mad_i32_i24 v145, v183, s54, v145
	global_store_dwordx2 v[144:145], v[140:141], off offset:128 nt
	global_store_dwordx2 v[144:145], v[142:143], off offset:160 nt
	v_pk_mul_f32 v[140:141], v[2:3], v[134:135]
	v_pk_mul_f32 v[134:135], v[6:7], v[134:135]
	v_pk_fma_f32 v[140:141], v[6:7], v[130:131], v[140:141] neg_lo:[0,0,1] neg_hi:[0,0,1]
	v_pk_mul_f32 v[142:143], v[4:5], v[136:137]
	v_pk_fma_f32 v[130:131], v[2:3], v[130:131], v[134:135]
	v_pk_mul_f32 v[134:135], v[8:9], v[136:137]
	v_pk_fma_f32 v[142:143], v[8:9], v[132:133], v[142:143] neg_lo:[0,0,1] neg_hi:[0,0,1]
	v_pk_fma_f32 v[132:133], v[4:5], v[132:133], v[134:135]
	v_pk_mul_f32 v[130:131], v[138:139], v[130:131] op_sel_hi:[0,1]
	v_pk_mul_f32 v[132:133], v[138:139], v[132:133] op_sel_hi:[0,1]
	v_cvt_pk_bf16_f32 v130, v130, v131
	v_cvt_pk_bf16_f32 v131, v132, v133
	v_or_b32_e32 v132, v180, v139
	v_pk_mul_f32 v[140:141], v[138:139], v[140:141] op_sel_hi:[0,1]
	v_pk_mul_f32 v[142:143], v[138:139], v[142:143] op_sel_hi:[0,1]
	v_mad_u64_u32 v[132:133], s[4:5], v132, s54, v[172:173]
	v_cvt_pk_bf16_f32 v140, v140, v141
	v_cvt_pk_bf16_f32 v141, v142, v143
	v_mad_i32_i24 v133, v181, s54, v133
	global_store_dwordx2 v[132:133], v[140:141], off offset:128 nt
	global_store_dwordx2 v[132:133], v[130:131], off offset:160 nt
	s_mov_b64 s[22:23], 0
.LBB0_446:
	s_andn2_b64 vcc, exec, s[22:23]
	s_cbranch_vccnz .LBB0_435
	v_cmp_gt_f32_e32 vcc, s53, v225
	s_lshl_b32 s4, s57, 2
	s_or_b32 s8, s4, s50
	v_cndmask_b32_e32 v130, v225, v226, vcc
	v_rsq_f32_e32 v130, v130
	s_ashr_i32 s4, s66, 9
	s_and_b32 s4, s4, -8
	s_add_i32 s6, s4, s8
	v_mul_f32_e32 v131, 0x45800000, v130
	v_cndmask_b32_e32 v130, v130, v131, vcc
	v_mul_f32_e32 v130, 0x3e16c740, v130
	s_ashr_i32 s7, s6, 31
	v_pk_mul_f32 v[118:119], v[118:119], v[130:131] op_sel_hi:[1,0]
	v_pk_mul_f32 v[120:121], v[120:121], v[130:131] op_sel_hi:[1,0]
	v_pk_mul_f32 v[114:115], v[114:115], v[130:131] op_sel_hi:[1,0]
	s_lshl_b64 s[4:5], s[6:7], 12
	v_cvt_pk_bf16_f32 v118, v118, v119
	v_cvt_pk_bf16_f32 v119, v120, v121
	v_cvt_pk_bf16_f32 v120, v114, v115
	v_pk_mul_f32 v[114:115], v[116:117], v[130:131] op_sel_hi:[1,0]
	s_or_b32 s6, s6, 2
	v_cmp_gt_f32_e32 vcc, s53, v223
	v_cvt_pk_bf16_f32 v121, v114, v115
	s_ashr_i32 s7, s6, 31
	v_cndmask_b32_e32 v115, v223, v224, vcc
	s_lshl_b64 s[6:7], s[6:7], 12
	v_rsq_f32_e32 v116, v115
	v_or_b32_e32 v114, s6, v222
	v_mad_u64_u32 v[114:115], s[22:23], v114, s54, v[170:171]
	v_mad_i32_i24 v115, s7, v207, v115
	global_store_dwordx4 v[114:115], v[118:121], off nt
	v_mul_f32_e32 v114, 0x45800000, v116
	v_cndmask_b32_e32 v114, v116, v114, vcc
	v_mul_f32_e32 v114, 0x3e16c740, v114
	v_pk_mul_f32 v[102:103], v[102:103], v[114:115] op_sel_hi:[1,0]
	v_pk_mul_f32 v[104:105], v[104:105], v[114:115] op_sel_hi:[1,0]
	v_pk_mul_f32 v[94:95], v[94:95], v[114:115] op_sel_hi:[1,0]
	v_cvt_pk_bf16_f32 v102, v102, v103
	v_cvt_pk_bf16_f32 v103, v104, v105
	v_cvt_pk_bf16_f32 v104, v94, v95
	v_pk_mul_f32 v[94:95], v[96:97], v[114:115] op_sel_hi:[1,0]
	v_cmp_gt_f32_e32 vcc, s53, v220
	v_cvt_pk_bf16_f32 v105, v94, v95
	v_or_b32_e32 v94, s6, v219
	v_cndmask_b32_e32 v95, v220, v221, vcc
	v_rsq_f32_e32 v96, v95
	v_mad_u64_u32 v[94:95], s[22:23], v94, s54, v[170:171]
	v_mad_i32_i24 v95, s7, v207, v95
	global_store_dwordx4 v[94:95], v[102:105], off nt
	v_mul_f32_e32 v94, 0x45800000, v96
	v_cndmask_b32_e32 v94, v96, v94, vcc
	v_mul_f32_e32 v102, 0x3e16c740, v94
	v_pk_mul_f32 v[86:87], v[86:87], v[102:103] op_sel_hi:[1,0]
	v_pk_mul_f32 v[88:89], v[88:89], v[102:103] op_sel_hi:[1,0]
	v_pk_mul_f32 v[78:79], v[78:79], v[102:103] op_sel_hi:[1,0]
	v_cvt_pk_bf16_f32 v86, v86, v87
	v_cvt_pk_bf16_f32 v87, v88, v89
	v_cvt_pk_bf16_f32 v88, v78, v79
	v_pk_mul_f32 v[78:79], v[80:81], v[102:103] op_sel_hi:[1,0]
	v_cmp_gt_f32_e32 vcc, s53, v217
	v_cvt_pk_bf16_f32 v89, v78, v79
	v_or_b32_e32 v78, s6, v216
	v_cndmask_b32_e32 v79, v217, v218, vcc
	v_rsq_f32_e32 v80, v79
	v_mad_u64_u32 v[78:79], s[22:23], v78, s54, v[170:171]
	v_mad_i32_i24 v79, s7, v207, v79
	global_store_dwordx4 v[78:79], v[86:89], off nt
	v_mul_f32_e32 v78, 0x45800000, v80
	v_cndmask_b32_e32 v78, v80, v78, vcc
	v_mul_f32_e32 v86, 0x3e16c740, v78
	v_pk_mul_f32 v[70:71], v[70:71], v[86:87] op_sel_hi:[1,0]
	v_pk_mul_f32 v[72:73], v[72:73], v[86:87] op_sel_hi:[1,0]
	v_pk_mul_f32 v[66:67], v[66:67], v[86:87] op_sel_hi:[1,0]
	v_pk_mul_f32 v[126:127], v[126:127], v[130:131] op_sel_hi:[1,0]
	v_pk_mul_f32 v[128:129], v[128:129], v[130:131] op_sel_hi:[1,0]
	v_pk_mul_f32 v[122:123], v[122:123], v[130:131] op_sel_hi:[1,0]
	v_pk_mul_f32 v[110:111], v[110:111], v[114:115] op_sel_hi:[1,0]
	v_pk_mul_f32 v[112:113], v[112:113], v[114:115] op_sel_hi:[1,0]
	v_pk_mul_f32 v[106:107], v[106:107], v[114:115] op_sel_hi:[1,0]
	v_pk_mul_f32 v[94:95], v[98:99], v[102:103] op_sel_hi:[1,0]
	v_pk_mul_f32 v[96:97], v[100:101], v[102:103] op_sel_hi:[1,0]
	v_pk_mul_f32 v[90:91], v[90:91], v[102:103] op_sel_hi:[1,0]
	v_pk_mul_f32 v[78:79], v[82:83], v[86:87] op_sel_hi:[1,0]
	v_pk_mul_f32 v[80:81], v[84:85], v[86:87] op_sel_hi:[1,0]
	v_pk_mul_f32 v[74:75], v[74:75], v[86:87] op_sel_hi:[1,0]
	v_cvt_pk_bf16_f32 v70, v70, v71
	v_cvt_pk_bf16_f32 v71, v72, v73
	v_cvt_pk_bf16_f32 v72, v66, v67
	v_pk_mul_f32 v[66:67], v[68:69], v[86:87] op_sel_hi:[1,0]
	v_mul_f32_e32 v68, 0x4b800000, v214
	v_cmp_gt_f32_e32 vcc, s53, v214
	v_cvt_pk_bf16_f32 v126, v126, v127
	v_cvt_pk_bf16_f32 v127, v128, v129
	v_cvt_pk_bf16_f32 v128, v122, v123
	v_pk_mul_f32 v[122:123], v[124:125], v[130:131] op_sel_hi:[1,0]
	v_cvt_pk_bf16_f32 v110, v110, v111
	v_cvt_pk_bf16_f32 v111, v112, v113
	v_cvt_pk_bf16_f32 v112, v106, v107
	v_pk_mul_f32 v[106:107], v[108:109], v[114:115] op_sel_hi:[1,0]
	v_cvt_pk_bf16_f32 v94, v94, v95
	v_cvt_pk_bf16_f32 v95, v96, v97
	v_cvt_pk_bf16_f32 v96, v90, v91
	v_pk_mul_f32 v[90:91], v[92:93], v[102:103] op_sel_hi:[1,0]
	v_cvt_pk_bf16_f32 v78, v78, v79
	v_cvt_pk_bf16_f32 v79, v80, v81
	v_cvt_pk_bf16_f32 v80, v74, v75
	v_pk_mul_f32 v[74:75], v[76:77], v[86:87] op_sel_hi:[1,0]
	v_cndmask_b32_e32 v68, v214, v68, vcc
	v_cvt_pk_bf16_f32 v129, v122, v123
	v_or_b32_e32 v122, s4, v222
	v_cvt_pk_bf16_f32 v113, v106, v107
	v_or_b32_e32 v106, s4, v219
	v_cvt_pk_bf16_f32 v97, v90, v91
	v_or_b32_e32 v90, s4, v216
	v_cvt_pk_bf16_f32 v81, v74, v75
	v_or_b32_e32 v74, s4, v215
	v_rsq_f32_e32 v68, v68
	v_mad_u64_u32 v[122:123], s[22:23], v122, s54, v[170:171]
	v_mad_u64_u32 v[106:107], s[22:23], v106, s54, v[170:171]
	v_mad_u64_u32 v[90:91], s[22:23], v90, s54, v[170:171]
	v_mad_u64_u32 v[74:75], s[22:23], v74, s54, v[170:171]
	v_cvt_pk_bf16_f32 v73, v66, v67
	v_or_b32_e32 v66, s6, v215
	v_mad_i32_i24 v123, s5, v207, v123
	v_mad_i32_i24 v107, s5, v207, v107
	v_mad_i32_i24 v91, s5, v207, v91
	v_mad_i32_i24 v75, s5, v207, v75
	v_mad_u64_u32 v[66:67], s[4:5], v66, s54, v[170:171]
	v_mad_i32_i24 v67, s7, v207, v67
	global_store_dwordx4 v[66:67], v[70:73], off nt
	v_mul_f32_e32 v67, 0x45800000, v68
	v_cndmask_b32_e32 v67, v68, v67, vcc
	v_and_b32_e32 v66, -8, v213
	v_mul_f32_e32 v68, 0x3e16c740, v67
	v_add_u32_e32 v66, s8, v66
	v_pk_mul_f32 v[62:63], v[62:63], v[68:69] op_sel_hi:[1,0]
	v_pk_mul_f32 v[64:65], v[64:65], v[68:69] op_sel_hi:[1,0]
	v_pk_mul_f32 v[58:59], v[58:59], v[68:69] op_sel_hi:[1,0]
	v_cvt_pk_bf16_f32 v62, v62, v63
	v_cvt_pk_bf16_f32 v63, v64, v65
	v_cvt_pk_bf16_f32 v64, v58, v59
	v_pk_mul_f32 v[58:59], v[60:61], v[68:69] op_sel_hi:[1,0]
	v_ashrrev_i32_e32 v67, 31, v66
	v_cvt_pk_bf16_f32 v65, v58, v59
	v_lshlrev_b64 v[58:59], 12, v[66:67]
	v_or_b32_e32 v60, v58, v209
	v_mad_u64_u32 v[60:61], s[4:5], v60, s54, v[170:171]
	v_pk_mul_f32 v[54:55], v[54:55], v[68:69] op_sel_hi:[1,0]
	v_pk_mul_f32 v[56:57], v[56:57], v[68:69] op_sel_hi:[1,0]
	v_pk_mul_f32 v[50:51], v[50:51], v[68:69] op_sel_hi:[1,0]
	v_mad_i32_i24 v61, v59, s54, v61
	v_cvt_pk_bf16_f32 v54, v54, v55
	v_cvt_pk_bf16_f32 v55, v56, v57
	v_cvt_pk_bf16_f32 v56, v50, v51
	v_pk_mul_f32 v[50:51], v[52:53], v[68:69] op_sel_hi:[1,0]
	global_store_dwordx4 v[122:123], v[126:129], off nt
	global_store_dwordx4 v[60:61], v[62:65], off nt
	v_cvt_pk_bf16_f32 v57, v50, v51
	v_or_b32_e32 v50, 2, v66
	v_mul_f32_e32 v60, 0x4b800000, v212
	v_cmp_gt_f32_e32 vcc, s53, v212
	v_ashrrev_i32_e32 v51, 31, v50
	v_lshlrev_b64 v[50:51], 12, v[50:51]
	v_cndmask_b32_e32 v60, v212, v60, vcc
	v_rsq_f32_e32 v60, v60
	v_or_b32_e32 v52, v50, v209
	v_mad_u64_u32 v[52:53], s[4:5], v52, s54, v[170:171]
	v_mad_i32_i24 v53, v51, s54, v53
	global_store_dwordx4 v[52:53], v[54:57], off nt
	v_mul_f32_e32 v52, 0x45800000, v60
	v_cndmask_b32_e32 v52, v60, v52, vcc
	v_or_b32_e32 v53, 16, v209
	v_mul_f32_e32 v52, 0x3e16c740, v52
	v_pk_mul_f32 v[38:39], v[38:39], v[52:53] op_sel_hi:[1,0]
	v_pk_mul_f32 v[40:41], v[40:41], v[52:53] op_sel_hi:[1,0]
	v_pk_mul_f32 v[34:35], v[34:35], v[52:53] op_sel_hi:[1,0]
	v_cvt_pk_bf16_f32 v38, v38, v39
	v_cvt_pk_bf16_f32 v39, v40, v41
	v_cvt_pk_bf16_f32 v40, v34, v35
	v_pk_mul_f32 v[34:35], v[36:37], v[52:53] op_sel_hi:[1,0]
	v_mul_f32_e32 v36, 0x4b800000, v211
	v_cmp_gt_f32_e32 vcc, s53, v211
	v_cvt_pk_bf16_f32 v41, v34, v35
	v_or_b32_e32 v34, v50, v53
	v_cndmask_b32_e32 v36, v211, v36, vcc
	v_rsq_f32_e32 v36, v36
	v_mad_u64_u32 v[34:35], s[4:5], v34, s54, v[170:171]
	v_mad_i32_i24 v35, v51, s54, v35
	global_store_dwordx4 v[106:107], v[110:113], off nt
	global_store_dwordx4 v[34:35], v[38:41], off nt
	v_mul_f32_e32 v34, 0x45800000, v36
	v_cndmask_b32_e32 v34, v36, v34, vcc
	v_or_b32_e32 v35, 32, v209
	v_mul_f32_e32 v34, 0x3e16c740, v34
	v_pk_mul_f32 v[22:23], v[22:23], v[34:35] op_sel_hi:[1,0]
	v_pk_mul_f32 v[24:25], v[24:25], v[34:35] op_sel_hi:[1,0]
	v_pk_mul_f32 v[18:19], v[18:19], v[34:35] op_sel_hi:[1,0]
	v_cvt_pk_bf16_f32 v22, v22, v23
	v_cvt_pk_bf16_f32 v23, v24, v25
	v_cvt_pk_bf16_f32 v24, v18, v19
	v_pk_mul_f32 v[18:19], v[20:21], v[34:35] op_sel_hi:[1,0]
	v_mul_f32_e32 v20, 0x4b800000, v210
	v_cmp_gt_f32_e32 vcc, s53, v210
	v_cvt_pk_bf16_f32 v25, v18, v19
	v_or_b32_e32 v18, v50, v35
	v_cndmask_b32_e32 v20, v210, v20, vcc
	v_rsq_f32_e32 v20, v20
	v_mad_u64_u32 v[18:19], s[4:5], v18, s54, v[170:171]
	v_mad_i32_i24 v19, v51, s54, v19
	global_store_dwordx4 v[90:91], v[94:97], off nt
	global_store_dwordx4 v[18:19], v[22:25], off nt
	v_mul_f32_e32 v18, 0x45800000, v20
	v_cndmask_b32_e32 v18, v20, v18, vcc
	v_or_b32_e32 v19, 48, v209
	v_mul_f32_e32 v18, 0x3e16c740, v18
	v_pk_mul_f32 v[46:47], v[46:47], v[52:53] op_sel_hi:[1,0]
	v_pk_mul_f32 v[48:49], v[48:49], v[52:53] op_sel_hi:[1,0]
	v_pk_mul_f32 v[42:43], v[42:43], v[52:53] op_sel_hi:[1,0]
	v_pk_mul_f32 v[30:31], v[30:31], v[34:35] op_sel_hi:[1,0]
	v_pk_mul_f32 v[32:33], v[32:33], v[34:35] op_sel_hi:[1,0]
	v_pk_mul_f32 v[26:27], v[26:27], v[34:35] op_sel_hi:[1,0]
	v_pk_mul_f32 v[14:15], v[14:15], v[18:19] op_sel_hi:[1,0]
	v_pk_mul_f32 v[16:17], v[16:17], v[18:19] op_sel_hi:[1,0]
	v_pk_mul_f32 v[10:11], v[10:11], v[18:19] op_sel_hi:[1,0]
	v_pk_mul_f32 v[6:7], v[6:7], v[18:19] op_sel_hi:[1,0]
	v_pk_mul_f32 v[8:9], v[8:9], v[18:19] op_sel_hi:[1,0]
	v_pk_mul_f32 v[2:3], v[2:3], v[18:19] op_sel_hi:[1,0]
	v_cvt_pk_bf16_f32 v46, v46, v47
	v_cvt_pk_bf16_f32 v47, v48, v49
	v_cvt_pk_bf16_f32 v48, v42, v43
	v_pk_mul_f32 v[42:43], v[44:45], v[52:53] op_sel_hi:[1,0]
	v_cvt_pk_bf16_f32 v30, v30, v31
	v_cvt_pk_bf16_f32 v31, v32, v33
	v_cvt_pk_bf16_f32 v32, v26, v27
	v_pk_mul_f32 v[26:27], v[28:29], v[34:35] op_sel_hi:[1,0]
	v_cvt_pk_bf16_f32 v14, v14, v15
	v_cvt_pk_bf16_f32 v15, v16, v17
	v_cvt_pk_bf16_f32 v16, v10, v11
	v_pk_mul_f32 v[10:11], v[12:13], v[18:19] op_sel_hi:[1,0]
	v_cvt_pk_bf16_f32 v6, v6, v7
	v_cvt_pk_bf16_f32 v7, v8, v9
	v_cvt_pk_bf16_f32 v8, v2, v3
	v_pk_mul_f32 v[2:3], v[4:5], v[18:19] op_sel_hi:[1,0]
	v_cvt_pk_bf16_f32 v49, v42, v43
	v_or_b32_e32 v42, v58, v53
	v_cvt_pk_bf16_f32 v33, v26, v27
	v_or_b32_e32 v26, v58, v35
	v_cvt_pk_bf16_f32 v17, v10, v11
	v_or_b32_e32 v10, v58, v19
	v_cvt_pk_bf16_f32 v9, v2, v3
	v_or_b32_e32 v2, v50, v19
	v_mad_u64_u32 v[42:43], s[4:5], v42, s54, v[170:171]
	v_mad_u64_u32 v[26:27], s[4:5], v26, s54, v[170:171]
	v_mad_u64_u32 v[10:11], s[4:5], v10, s54, v[170:171]
	v_mad_u64_u32 v[2:3], s[4:5], v2, s54, v[170:171]
	v_mad_i32_i24 v43, v59, s54, v43
	v_mad_i32_i24 v27, v59, s54, v27
	v_mad_i32_i24 v11, v59, s54, v11
	v_mad_i32_i24 v3, v51, s54, v3
	global_store_dwordx4 v[74:75], v[78:81], off nt
	global_store_dwordx4 v[42:43], v[46:49], off nt
	global_store_dwordx4 v[26:27], v[30:33], off nt
	global_store_dwordx4 v[10:11], v[14:17], off nt
	global_store_dwordx4 v[2:3], v[6:9], off nt
	s_branch .LBB0_435

.LBB0_499:
	s_or_b64 exec, exec, s[14:15]
	s_waitcnt lgkmcnt(0)
	s_barrier
	ds_read_b128 v[2:5], v58 offset:34816
	ds_read_b128 v[6:9], v58
	ds_read_b128 v[10:13], v58 offset:16
	ds_read_b128 v[14:17], v58 offset:34832
	ds_read_b128 v[36:39], v59
	ds_read_b128 v[40:43], v59 offset:16
	s_waitcnt lgkmcnt(5)
	v_exp_f32_e32 v44, v2
	v_exp_f32_e64 v2, -v2
	v_exp_f32_e32 v45, v3
	v_exp_f32_e64 v3, -v3
	v_exp_f32_e32 v68, v4
	v_exp_f32_e64 v4, -v4
	v_exp_f32_e32 v69, v5
	v_exp_f32_e64 v5, -v5
	s_waitcnt lgkmcnt(1)
	v_pk_mul_f32 v[36:37], v[2:3], v[36:37]
	v_exp_f32_e32 v2, v14
	v_exp_f32_e32 v3, v15
	v_pk_mul_f32 v[38:39], v[4:5], v[38:39]
	v_exp_f32_e64 v4, -v14
	v_exp_f32_e64 v5, -v15
	v_exp_f32_e32 v14, v16
	v_exp_f32_e32 v15, v17
	v_exp_f32_e64 v16, -v16
	v_exp_f32_e64 v17, -v17
	v_pk_mul_f32 v[6:7], v[6:7], v[44:45]
	v_pk_mul_f32 v[8:9], v[8:9], v[68:69]
	v_pk_mul_f32 v[10:11], v[10:11], v[2:3]
	v_pk_mul_f32 v[12:13], v[12:13], v[14:15]
	s_waitcnt lgkmcnt(0)
	v_pk_mul_f32 v[40:41], v[4:5], v[40:41]
	v_pk_mul_f32 v[14:15], v[16:17], v[42:43]
	v_cvt_pk_bf16_f32 v2, v6, v7
	v_cvt_pk_bf16_f32 v3, v8, v9
	v_cvt_pk_bf16_f32 v4, v10, v11
	v_cvt_pk_bf16_f32 v5, v12, v13
	v_lshl_add_u64 v[6:7], s[8:9], 0, v[32:33]
	global_store_dwordx4 v[6:7], v[2:5], off nt
	v_lshl_add_u64 v[6:7], s[10:11], 0, v[32:33]
	s_nop 0
	v_cvt_pk_bf16_f32 v2, v36, v37
	v_cvt_pk_bf16_f32 v3, v38, v39
	v_cvt_pk_bf16_f32 v4, v40, v41
	v_cvt_pk_bf16_f32 v5, v14, v15
	global_store_dwordx4 v[6:7], v[2:5], off
	ds_read_b128 v[2:5], v61 offset:34816
	ds_read_b128 v[6:9], v61
	ds_read_b128 v[10:13], v61 offset:16
	ds_read_b128 v[14:17], v61 offset:34832
	ds_read_b128 v[36:39], v62
	ds_read_b128 v[40:43], v62 offset:16
	s_waitcnt lgkmcnt(5)
	v_exp_f32_e32 v32, v2
	v_exp_f32_e64 v2, -v2
	v_exp_f32_e32 v33, v3
	v_exp_f32_e64 v3, -v3
	v_exp_f32_e32 v44, v4
	v_exp_f32_e64 v4, -v4
	v_exp_f32_e32 v45, v5
	v_exp_f32_e64 v5, -v5
	s_waitcnt lgkmcnt(4)
	v_pk_mul_f32 v[6:7], v[6:7], v[32:33]
	s_waitcnt lgkmcnt(1)
	v_pk_mul_f32 v[32:33], v[2:3], v[36:37]
	v_exp_f32_e32 v2, v14
	v_pk_mul_f32 v[36:37], v[4:5], v[38:39]
	v_exp_f32_e64 v4, -v14
	v_exp_f32_e32 v3, v15
	v_exp_f32_e64 v5, -v15
	v_exp_f32_e32 v14, v16
	v_exp_f32_e32 v15, v17
	v_exp_f32_e64 v16, -v16
	v_exp_f32_e64 v17, -v17
	v_pk_mul_f32 v[8:9], v[8:9], v[44:45]
	v_pk_mul_f32 v[10:11], v[10:11], v[2:3]
	v_pk_mul_f32 v[12:13], v[12:13], v[14:15]
	s_waitcnt lgkmcnt(0)
	v_pk_mul_f32 v[38:39], v[4:5], v[40:41]
	v_pk_mul_f32 v[14:15], v[16:17], v[42:43]
	v_cvt_pk_bf16_f32 v2, v6, v7
	v_cvt_pk_bf16_f32 v3, v8, v9
	v_cvt_pk_bf16_f32 v4, v10, v11
	v_cvt_pk_bf16_f32 v5, v12, v13
	v_lshl_add_u64 v[6:7], s[8:9], 0, v[34:35]
	global_store_dwordx4 v[6:7], v[2:5], off nt
	v_lshl_add_u64 v[6:7], s[10:11], 0, v[34:35]
	s_nop 0
	v_cvt_pk_bf16_f32 v2, v32, v33
	v_cvt_pk_bf16_f32 v3, v36, v37
	v_cvt_pk_bf16_f32 v4, v38, v39
	v_cvt_pk_bf16_f32 v5, v14, v15
	global_store_dwordx4 v[6:7], v[2:5], off

.LBB0_571:
	v_lshl_add_u64 v[2:3], s[62:63], 0, v[50:51]
	v_lshl_add_u64 v[6:7], s[62:63], 0, v[56:57]
	v_lshl_add_u64 v[8:9], s[62:63], 0, v[60:61]
	v_lshl_add_u64 v[104:105], s[62:63], 0, v[62:63]
	v_lshl_add_u64 v[22:23], s[62:63], 0, v[80:81]
	v_lshl_add_u64 v[32:33], s[62:63], 0, v[38:39]
	v_lshl_add_u64 v[4:5], s[62:63], 0, v[58:59]
	v_lshl_add_u64 v[106:107], s[62:63], 0, v[66:67]
	v_lshl_add_u64 v[110:111], s[62:63], 0, v[68:69]
	v_lshl_add_u64 v[112:113], s[62:63], 0, v[70:71]
	v_lshl_add_u64 v[116:117], s[62:63], 0, v[72:73]
	v_lshl_add_u64 v[114:115], s[62:63], 0, v[74:75]
	v_lshl_add_u64 v[118:119], s[62:63], 0, v[76:77]
	v_lshl_add_u64 v[108:109], s[62:63], 0, v[78:79]
	v_lshl_add_u64 v[14:15], s[62:63], 0, v[42:43]
	v_lshl_add_u64 v[24:25], s[62:63], 0, v[82:83]
	v_lshl_add_u64 v[28:29], s[62:63], 0, v[84:85]
	v_lshl_add_u64 v[98:99], s[62:63], 0, v[86:87]
	v_lshl_add_u64 v[12:13], s[62:63], 0, v[88:89]
	v_lshl_add_u64 v[18:19], s[62:63], 0, v[90:91]
	v_lshl_add_u64 v[10:11], s[62:63], 0, v[92:93]
	v_lshl_add_u64 v[16:17], s[62:63], 0, v[54:55]
	v_lshl_add_u64 v[20:21], s[62:63], 0, v[52:53]
	v_lshl_add_u64 v[26:27], s[62:63], 0, v[48:49]
	v_lshl_add_u64 v[96:97], s[62:63], 0, v[46:47]
	v_lshl_add_u64 v[100:101], s[62:63], 0, v[44:45]
	v_lshl_add_u64 v[30:31], s[62:63], 0, v[40:41]
	global_load_ushort v138, v[104:105], off
	global_load_ushort v142, v[106:107], off
	global_load_ushort v143, v[110:111], off
	global_load_ushort v139, v[112:113], off
	global_load_ushort v157, v[116:117], off
	global_load_ushort v140, v[114:115], off
	global_load_ushort v162, v[118:119], off
	global_load_ushort v141, v[108:109], off
	global_load_ushort v163, v[2:3], off offset:-2048
	global_load_ushort v164, v[2:3], off offset:-1024
	global_load_ushort v165, v[2:3], off
	global_load_ushort v166, v[2:3], off offset:1024
	global_load_ushort v167, v[6:7], off
	s_nop 0
	global_load_ushort v6, v[4:5], off
	global_load_ushort v7, v[8:9], off
	global_load_ushort v168, v[2:3], off offset:-1984
	global_load_ushort v169, v[22:23], off
	global_load_ushort v170, v[14:15], off offset:-1024
	global_load_ushort v171, v[14:15], off
	s_nop 0
	global_load_ushort v22, v[14:15], off offset:1024
	global_load_ushort v23, v[24:25], off
	global_load_ushort v172, v[28:29], off
	global_load_ushort v8, v[98:99], off
	global_load_ushort v9, v[12:13], off
	global_load_ushort v173, v[18:19], off
	global_load_ushort v174, v[10:11], off
	global_load_ushort v175, v[16:17], off
	global_load_ushort v176, v[20:21], off
	global_load_ushort v177, v[26:27], off
	global_load_ushort v178, v[96:97], off
	global_load_ushort v179, v[100:101], off
	global_load_ushort v180, v[30:31], off
	v_add_co_u32_e32 v2, vcc, s11, v32
	v_lshl_add_u64 v[102:103], s[62:63], 0, v[36:37]
	s_nop 0
	v_addc_co_u32_e32 v3, vcc, 0, v33, vcc
	v_add_co_u32_e32 v4, vcc, s12, v102
	v_lshl_add_u64 v[126:127], s[62:63], 0, v[34:35]
	s_nop 0
	v_addc_co_u32_e32 v5, vcc, 0, v103, vcc
	v_add_co_u32_e32 v144, vcc, s14, v126
	v_cvt_pk_bf16_f32 v120, v64, v65
	s_nop 0
	v_addc_co_u32_e32 v145, vcc, 0, v127, vcc
	v_add_co_u32_e32 v146, vcc, s15, v126
	v_cvt_pk_bf16_f32 v121, v94, v95
	s_nop 0
	v_addc_co_u32_e32 v147, vcc, 0, v127, vcc
	v_add_co_u32_e32 v148, vcc, s16, v126
	s_add_i32 s10, s10, -1
	s_nop 0
	v_addc_co_u32_e32 v149, vcc, 0, v127, vcc
	v_add_co_u32_e32 v150, vcc, s17, v126
	v_lshl_add_u64 v[34:35], v[34:35], 0, s[2:3]
	s_nop 0
	v_addc_co_u32_e32 v151, vcc, 0, v127, vcc
	v_add_co_u32_e32 v152, vcc, s18, v126
	s_waitcnt vmcnt(0)
	v_perm_b32 v139, v157, v139, s13
	v_addc_co_u32_e32 v153, vcc, 0, v127, vcc
	v_add_co_u32_e32 v154, vcc, s19, v126
	v_perm_b32 v140, v162, v140, s13
	s_nop 0
	v_addc_co_u32_e32 v155, vcc, 0, v127, vcc
	v_add_co_u32_e32 v158, vcc, s20, v126
	v_lshl_add_u64 v[36:37], v[36:37], 0, s[4:5]
	s_nop 0
	v_addc_co_u32_e32 v159, vcc, 0, v127, vcc
	v_add_co_u32_e32 v160, vcc, s21, v126
	v_lshl_add_u64 v[38:39], v[38:39], 0, s[6:7]
	s_nop 0
	v_addc_co_u32_e32 v161, vcc, 0, v127, vcc
	global_load_dwordx4 v[18:21], v[2:3], off offset:1024
	global_load_dwordx4 v[96:99], v[2:3], off offset:1056
	global_load_dwordx4 v[100:103], v[4:5], off offset:1024
	global_load_dwordx4 v[104:107], v[4:5], off offset:1280
	global_load_dwordx4 v[108:111], v[4:5], off offset:1536
	global_load_dwordx4 v[112:115], v[4:5], off offset:1792
	global_load_dwordx4 v[116:119], v[4:5], off offset:2048
	global_load_dwordx4 v[126:129], v[4:5], off offset:2304
	global_load_dwordx4 v[130:133], v[4:5], off offset:2560
	global_load_dwordx4 v[134:137], v[4:5], off offset:2816
	v_perm_b32 v5, v138, v7, s13
	v_perm_b32 v4, v6, v167, s13
	v_perm_b32 v3, v166, v165, s13
	v_perm_b32 v2, v164, v163, s13
	v_perm_b32 v141, v169, v141, s13
	v_perm_b32 v138, v143, v142, s13
	v_perm_b32 v24, v172, v23, s13
	v_perm_b32 v23, v22, v171, s13
	v_perm_b32 v22, v170, v168, s13
	s_waitcnt lgkmcnt(0)
	s_barrier
	v_perm_b32 v25, v9, v8, s13
	s_waitcnt vmcnt(9)
	v_mfma_f32_32x32x16_bf16 v[2:17], v[2:5], v[18:21], 0
	v_perm_b32 v143, v180, v179, s13
	v_perm_b32 v142, v178, v177, s13
	v_lshl_add_u64 v[40:41], v[40:41], 0, s[8:9]
	v_lshl_add_u64 v[42:43], v[42:43], 0, s[8:9]
	v_lshl_add_u64 v[44:45], v[44:45], 0, s[8:9]
	v_lshl_add_u64 v[46:47], v[46:47], 0, s[8:9]
	v_lshl_add_u64 v[48:49], v[48:49], 0, s[8:9]
	v_mfma_f32_32x32x16_bf16 v[18:33], v[22:25], v[18:21], 0
	v_lshl_add_u64 v[50:51], v[50:51], 0, s[8:9]
	v_lshl_add_u64 v[52:53], v[52:53], 0, s[8:9]
	v_lshl_add_u64 v[54:55], v[54:55], 0, s[8:9]
	v_lshl_add_u64 v[56:57], v[56:57], 0, s[8:9]
	v_lshl_add_u64 v[58:59], v[58:59], 0, s[8:9]
	v_lshl_add_u64 v[60:61], v[60:61], 0, s[8:9]
	v_lshl_add_u64 v[62:63], v[62:63], 0, s[8:9]
	s_waitcnt vmcnt(8)
	v_mfma_f32_32x32x16_bf16 v[2:17], v[138:141], v[96:99], v[2:17]
	v_perm_b32 v141, v176, v175, s13
	v_perm_b32 v140, v174, v173, s13
	v_lshl_add_u64 v[66:67], v[66:67], 0, s[8:9]
	v_lshl_add_u64 v[68:69], v[68:69], 0, s[8:9]
	v_lshl_add_u64 v[70:71], v[70:71], 0, s[8:9]
	v_lshl_add_u64 v[72:73], v[72:73], 0, s[8:9]
	v_lshl_add_u64 v[74:75], v[74:75], 0, s[8:9]
	v_mfma_f32_32x32x16_bf16 v[18:33], v[140:143], v[96:99], v[18:33]
	s_nop 3
	ds_write_b128 v1, v[2:5]
	ds_write_b128 v1, v[6:9] offset:32
	ds_write_b128 v1, v[10:13] offset:64
	ds_write_b128 v1, v[14:17] offset:96
	s_nop 3
	ds_write_b128 v1, v[18:21] offset:128
	ds_write_b128 v1, v[22:25] offset:160
	ds_write_b128 v1, v[26:29] offset:192
	ds_write_b128 v1, v[30:33] offset:224
	s_waitcnt lgkmcnt(0)
	s_barrier
	global_store_dwordx2 v[144:145], v[120:121], off offset:1024 nt
	ds_read_b128 v[2:5], v125
	ds_read_b128 v[6:9], v125 offset:8704
	ds_read_b128 v[10:13], v125 offset:17408
	ds_read_b128 v[14:17], v125 offset:26112
	ds_read_b128 v[18:21], v125 offset:34816
	ds_read_b128 v[22:25], v125 offset:43520
	ds_read_b128 v[26:29], v125 offset:52224
	ds_read_b128 v[30:33], v125 offset:60928
	s_waitcnt lgkmcnt(7)
	v_pk_add_f32 v[2:3], v[64:65], v[2:3]
	v_pk_add_f32 v[4:5], v[94:95], v[4:5]
	s_waitcnt vmcnt(8)
	v_pk_mul_f32 v[94:95], v[100:101], v[2:3]
	v_pk_mul_f32 v[64:65], v[102:103], v[4:5]
	s_waitcnt lgkmcnt(6)
	v_pk_fma_f32 v[2:3], v[100:101], v[2:3], v[6:7]
	v_pk_fma_f32 v[4:5], v[102:103], v[4:5], v[8:9]
	v_cvt_pk_bf16_f32 v6, v94, v95
	v_cvt_pk_bf16_f32 v7, v64, v65
	s_waitcnt vmcnt(7)
	v_pk_mul_f32 v[8:9], v[106:107], v[4:5]
	v_pk_mul_f32 v[64:65], v[104:105], v[2:3]
	s_waitcnt lgkmcnt(5)
	v_pk_fma_f32 v[4:5], v[106:107], v[4:5], v[12:13]
	v_pk_fma_f32 v[2:3], v[104:105], v[2:3], v[10:11]
	global_store_dwordx2 v[146:147], v[6:7], off offset:1024 nt
	v_cvt_pk_bf16_f32 v6, v64, v65
	v_cvt_pk_bf16_f32 v7, v8, v9
	s_waitcnt vmcnt(7)
	v_pk_mul_f32 v[8:9], v[110:111], v[4:5]
	v_pk_mul_f32 v[10:11], v[108:109], v[2:3]
	s_waitcnt lgkmcnt(4)
	v_pk_fma_f32 v[4:5], v[110:111], v[4:5], v[16:17]
	v_pk_fma_f32 v[2:3], v[108:109], v[2:3], v[14:15]
	global_store_dwordx2 v[148:149], v[6:7], off offset:1024 nt
	v_cvt_pk_bf16_f32 v6, v10, v11
	v_cvt_pk_bf16_f32 v7, v8, v9
	s_waitcnt vmcnt(7)
	v_pk_mul_f32 v[8:9], v[114:115], v[4:5]
	v_pk_mul_f32 v[10:11], v[112:113], v[2:3]
	s_waitcnt lgkmcnt(3)
	v_pk_fma_f32 v[4:5], v[114:115], v[4:5], v[20:21]
	v_pk_fma_f32 v[2:3], v[112:113], v[2:3], v[18:19]
	global_store_dwordx2 v[150:151], v[6:7], off offset:1024 nt
	v_cvt_pk_bf16_f32 v6, v10, v11
	v_cvt_pk_bf16_f32 v7, v8, v9
	s_waitcnt vmcnt(7)
	v_pk_mul_f32 v[8:9], v[118:119], v[4:5]
	v_pk_mul_f32 v[10:11], v[116:117], v[2:3]
	s_waitcnt lgkmcnt(2)
	v_pk_fma_f32 v[4:5], v[118:119], v[4:5], v[24:25]
	v_pk_fma_f32 v[2:3], v[116:117], v[2:3], v[22:23]
	global_store_dwordx2 v[152:153], v[6:7], off offset:1024 nt
	v_cvt_pk_bf16_f32 v6, v10, v11
	v_cvt_pk_bf16_f32 v7, v8, v9
	s_waitcnt vmcnt(7)
	v_pk_mul_f32 v[8:9], v[128:129], v[4:5]
	v_pk_mul_f32 v[10:11], v[126:127], v[2:3]
	s_waitcnt lgkmcnt(1)
	v_pk_fma_f32 v[4:5], v[128:129], v[4:5], v[28:29]
	v_pk_fma_f32 v[2:3], v[126:127], v[2:3], v[26:27]
	global_store_dwordx2 v[154:155], v[6:7], off offset:1024 nt
	v_cvt_pk_bf16_f32 v6, v10, v11
	v_cvt_pk_bf16_f32 v7, v8, v9
	s_waitcnt vmcnt(7)
	v_pk_mul_f32 v[8:9], v[132:133], v[4:5]
	v_pk_mul_f32 v[10:11], v[130:131], v[2:3]
	s_waitcnt lgkmcnt(0)
	v_pk_fma_f32 v[4:5], v[132:133], v[4:5], v[32:33]
	v_pk_fma_f32 v[2:3], v[130:131], v[2:3], v[30:31]
	v_lshl_add_u64 v[76:77], v[76:77], 0, s[8:9]
	v_lshl_add_u64 v[78:79], v[78:79], 0, s[8:9]
	v_lshl_add_u64 v[80:81], v[80:81], 0, s[8:9]
	v_lshl_add_u64 v[82:83], v[82:83], 0, s[8:9]
	v_lshl_add_u64 v[84:85], v[84:85], 0, s[8:9]
	v_lshl_add_u64 v[86:87], v[86:87], 0, s[8:9]
	v_lshl_add_u64 v[88:89], v[88:89], 0, s[8:9]
	v_lshl_add_u64 v[90:91], v[90:91], 0, s[8:9]
	v_lshl_add_u64 v[92:93], v[92:93], 0, s[8:9]
	s_cmp_eq_u32 s10, 0
	global_store_dwordx2 v[158:159], v[6:7], off offset:1024 nt
	v_cvt_pk_bf16_f32 v6, v10, v11
	v_cvt_pk_bf16_f32 v7, v8, v9
	s_waitcnt vmcnt(7)
	v_pk_mul_f32 v[94:95], v[136:137], v[4:5]
	v_pk_mul_f32 v[64:65], v[134:135], v[2:3]
	global_store_dwordx2 v[160:161], v[6:7], off offset:1024 nt
	s_cbranch_scc0 .LBB0_571
	s_waitcnt vmcnt(0)
	s_barrier
	s_and_saveexec_b64 s[2:3], s[44:45]
	s_cbranch_execz .LBB0_576
	s_mov_b64 s[4:5], exec
	buffer_wbl2 sc1
	s_waitcnt vmcnt(0)
	s_waitcnt vmcnt(0)
	v_mbcnt_lo_u32_b32 v1, s4, 0
	v_mbcnt_hi_u32_b32 v1, s5, v1
	v_cmp_eq_u32_e32 vcc, 0, v1
	s_and_saveexec_b64 s[6:7], vcc
	s_cbranch_execz .LBB0_575
	s_lshl_b64 s[0:1], s[0:1], 2
	s_add_u32 s0, s46, s0
	s_addc_u32 s1, s47, s1
	s_bcnt1_i32_b64 s4, s[4:5]
	v_mov_b32_e32 v1, 0
	v_mov_b32_e32 v2, s4
	global_atomic_add v1, v2, s[0:1]
	global_atomic_add v1, v2, s[46:47] offset:256
